# conv phase work redistributed: blocks that ran 5 dilated-attention units take 8 conv slots, blocks with 4 units take 28 (absorbs the dil imbalance)
# speedup vs baseline: 1.0026x; 1.0026x over previous
; __device__ __forceinline__ void conv_phase(bf16_t* proj, const float* cw, int G) {
;     int tid_ = threadIdx.x; asm volatile("" : "+v"(tid_));
;     for (int item = blockIdx.x * 512 + tid_; item < M * 48; item += G * 512) {
;         const int row = item / 48, ch = (item % 48) * 8, t = row % SEQ;
; __device__ __forceinline__ void attn_phase(unsigned char* ws, int l, LAS unsigned char* lds, int G) {
;     ...
;     const int vb = (G % 8 == 0) ? (bx % 8) * (G / 8) + bx / 8 : bx;
.LBB0_561:
	v_mov_b32_e32 v0, v154
	s_lshl_b32 s33, s14, 9
	s_lshl_b32 s95, s14, 9
	s_mov_b32 s93, 0x240000
	s_lshl_b32 s94, s74, 9
	s_cmpk_lg_u32 s74, 0x100
	s_cbranch_scc1 .Lcv0_go
	s_and_b32 s92, s14, 7
	s_lshl_b32 s92, s92, 5
	s_lshr_b32 s95, s14, 3
	s_add_i32 s92, s92, s95
	s_mov_b32 s94, 0x10000
	s_cmpk_lt_u32 s92, 0x80
	s_cbranch_scc1 .Lcv0_heavy
	s_addk_i32 s92, 0x380
	s_lshl_b32 s95, s92, 9
	s_branch .Lcv0_go
.Lcv0_heavy:
	s_lshl_b32 s95, s92, 9
	s_mov_b32 s93, 0x80000
.Lcv0_go:
	s_mov_b32 s2, s93
	v_add_u32_e32 v1, s95, v0
	v_cmp_gt_i32_e32 vcc, s2, v1
	s_and_saveexec_b64 s[2:3], vcc
	s_cbranch_execz .LBB0_570
	s_mov_b32 s10, s94
	v_lshlrev_b32_e32 v0, 3, v1
	s_lshl_b32 s11, s94, 3
	s_mov_b64 s[6:7], 0
	s_mov_b32 s12, 0x2aaaaaab
	s_movk_i32 s13, 0xfe80
	s_movk_i32 s15, 0x1800
	v_mov_b64_e32 v[2:3], s[48:49]
	s_movk_i32 s16, 0xbfff
	s_add_i32 s17, s93, -1
	s_branch .LBB0_564

; __device__ __forceinline__ void conv_phase(bf16_t* proj, const float* cw, int G) {
;     int tid_ = threadIdx.x; asm volatile("" : "+v"(tid_));
;     for (int item = blockIdx.x * 512 + tid_; item < M * 48; item += G * 512) {
;         const int row = item / 48, ch = (item % 48) * 8, t = row % SEQ;
; __device__ __forceinline__ void attn_phase(unsigned char* ws, int l, LAS unsigned char* lds, int G) {
;     ...
;     const int vb = (G % 8 == 0) ? (bx % 8) * (G / 8) + bx / 8 : bx;
.LBB0_1273:
	v_mov_b32_e32 v0, v154
	s_lshl_b32 s95, s14, 9
	s_mov_b32 s93, 0x240000
	s_lshl_b32 s94, s74, 9
	s_cmpk_lg_u32 s74, 0x100
	s_cbranch_scc1 .Lcv1_go
	s_and_b32 s92, s14, 7
	s_lshl_b32 s92, s92, 5
	s_lshr_b32 s95, s14, 3
	s_add_i32 s92, s92, s95
	s_mov_b32 s94, 0x10000
	s_cmpk_lt_u32 s92, 0x80
	s_cbranch_scc1 .Lcv1_heavy
	s_addk_i32 s92, 0x380
	s_lshl_b32 s95, s92, 9
	s_branch .Lcv1_go

; __device__ __forceinline__ void conv_phase(bf16_t* proj, const float* cw, int G) {
;     int tid_ = threadIdx.x; asm volatile("" : "+v"(tid_));
;     for (int item = blockIdx.x * 512 + tid_; item < M * 48; item += G * 512) {
;         const int row = item / 48, ch = (item % 48) * 8, t = row % SEQ;
.Lcv1_go:
	s_mov_b32 s4, s93
	v_add_u32_e32 v1, s95, v0
	v_cmp_gt_i32_e32 vcc, s4, v1
	s_and_saveexec_b64 s[4:5], vcc
	s_cbranch_execz .LBB0_1282
	s_add_u32 s8, s40, 0xc1200
	s_addc_u32 s9, s41, 0
	s_mov_b32 s15, s94
	v_lshlrev_b32_e32 v0, 3, v1
	s_lshl_b32 s16, s94, 3
	s_mov_b64 s[10:11], 0
	s_mov_b32 s17, 0x2aaaaaab
	s_movk_i32 s18, 0xfe80
	s_movk_i32 s19, 0x1800
	v_mov_b64_e32 v[2:3], s[44:45]
	s_movk_i32 s20, 0xbfff
	s_add_i32 s21, s93, -1
	s_branch .LBB0_1276
